# NSA units: Q fragments of both head pairs loaded early (under the previous branch epilogue / the top-k selection) instead of in the branch header
# speedup vs baseline: 1.0067x; 1.0067x over previous
.LBB0_612:
	s_and_b64 s[0:1], s[2:3], exec
	s_cselect_b32 s0, 20, 0
	s_lshl_b32 s1, s26, 2
	s_add_i32 s0, s0, s1
	s_and_b64 vcc, s[2:3], exec
	s_cselect_b32 s1, 0, 1
	s_ashr_i32 s20, s25, 8
	s_mul_i32 s1, s1, s20
	s_lshl_b32 s1, s1, 1
	s_add_i32 s20, s0, s1
	v_add_u32_e32 v4, s27, v194
	v_ashrrev_i32_e32 v5, 31, v4
	v_lshlrev_b64 v[4:5], 7, v[4:5]
	v_lshl_add_u64 v[4:5], s[86:87], 0, v[4:5]
	v_lshrrev_b32_e32 v6, 1, v192
	v_and_b32_e32 v6, 16, v6
	v_mov_b32_e32 v7, 0
	v_lshl_add_u64 v[6:7], v[4:5], 0, v[6:7]
	s_add_i32 s0, s20, 0
	s_ashr_i32 s1, s0, 31
	s_lshl_b64 s[0:1], s[0:1], 23
	v_lshl_add_u64 v[4:5], v[6:7], 0, s[0:1]
	global_load_dwordx4 v[134:137], v[4:5], off
	global_load_dwordx4 v[138:141], v[4:5], off offset:32
	global_load_dwordx4 v[142:145], v[4:5], off offset:64
	global_load_dwordx4 v[150:153], v[4:5], off offset:96
	s_add_i32 s0, s20, 1
	s_ashr_i32 s1, s0, 31
	s_lshl_b64 s[0:1], s[0:1], 23
	v_lshl_add_u64 v[4:5], v[6:7], 0, s[0:1]
	global_load_dwordx4 v[146:149], v[4:5], off
	global_load_dwordx4 v[154:157], v[4:5], off offset:32
	global_load_dwordx4 v[158:161], v[4:5], off offset:64
	global_load_dwordx4 v[162:165], v[4:5], off offset:96
	s_and_b64 vcc, exec, s[4:5]
	s_mov_b32 s11, 0
	s_cbranch_vccnz .LBB0_618
	s_ashr_i32 s0, s33, 6
	v_mov_b32_e32 v196, -1
	s_cmp_lt_i32 s0, 16
	v_mov_b32_e32 v19, -1
	s_cbranch_scc1 .LBB0_619
	ds_read_b128 v[4:7], v193
	ds_read_b128 v[8:11], v193 offset:1024
	s_movk_i32 s20, 0x7f
	v_cmp_lt_u32_e32 vcc, 31, v84
	s_add_i32 s1, s0, -2
	s_waitcnt lgkmcnt(0)
	v_and_b32_e32 v3, 0xffffffc0, v4
	v_xad_u32 v3, v85, s20, v3
	v_cndmask_b32_e32 v4, 0, v3, vcc
	v_and_b32_e32 v3, 0xffffffc0, v5
	v_sub_u32_e32 v3, v3, v85
	v_add_u32_e32 v5, 0x7d, v3
	v_and_b32_e32 v3, 0xffffffc0, v6
	v_sub_u32_e32 v3, v3, v85
	v_add_u32_e32 v6, 0x7b, v3
	v_and_b32_e32 v3, 0xffffffc0, v7
	v_sub_u32_e32 v3, v3, v85
	v_add_u32_e32 v7, 0x79, v3
	v_and_b32_e32 v3, 0xffffffc0, v8
	v_sub_u32_e32 v3, v3, v85
	ds_write_b128 v193, v[4:7]
	v_add_u32_e32 v4, 0x77, v3
	v_and_b32_e32 v3, 0xffffffc0, v9
	v_sub_u32_e32 v3, v3, v85
	v_add_u32_e32 v5, 0x75, v3
	v_and_b32_e32 v3, 0xffffffc0, v10
	v_sub_u32_e32 v3, v3, v85
	v_and_b32_e32 v7, 0xffffffc0, v11
	ds_read_b128 v[8:11], v193 offset:2048
	v_add_u32_e32 v6, 0x73, v3
	v_or_b32_e32 v3, 14, v85
	s_movk_i32 s20, 0x71
	v_xad_u32 v7, v85, s20, v7
	v_cmp_ge_i32_e32 vcc, s1, v3
	v_or_b32_e32 v3, 16, v85
	s_movk_i32 s20, 0x6f
	v_cndmask_b32_e32 v7, 0, v7, vcc
	ds_write_b128 v193, v[4:7] offset:1024
	ds_read_b128 v[4:7], v193 offset:3072
	s_waitcnt lgkmcnt(0)
	v_and_b32_e32 v8, 0xffffffc0, v8
	v_xad_u32 v8, v85, s20, v8
	v_cmp_ge_i32_e32 vcc, s1, v3
	v_or_b32_e32 v3, 18, v85
	v_and_b32_e32 v9, 0xffffffc0, v9
	s_movk_i32 s20, 0x6d
	v_cndmask_b32_e32 v8, 0, v8, vcc
	v_xad_u32 v9, v85, s20, v9
	v_cmp_ge_i32_e32 vcc, s1, v3
	v_or_b32_e32 v3, 20, v85
	v_and_b32_e32 v10, 0xffffffc0, v10
	s_movk_i32 s20, 0x6b
	v_cndmask_b32_e32 v9, 0, v9, vcc
	v_xad_u32 v10, v85, s20, v10
	v_cmp_ge_i32_e32 vcc, s1, v3
	v_or_b32_e32 v3, 22, v85
	v_and_b32_e32 v11, 0xffffffc0, v11
	s_movk_i32 s20, 0x69
	v_cndmask_b32_e32 v10, 0, v10, vcc
	v_xad_u32 v11, v85, s20, v11
	v_cmp_ge_i32_e32 vcc, s1, v3
	v_or_b32_e32 v3, 24, v85
	v_and_b32_e32 v4, 0xffffffc0, v4
	s_movk_i32 s20, 0x67
	v_cndmask_b32_e32 v11, 0, v11, vcc
	v_xad_u32 v4, v85, s20, v4
	v_cmp_ge_i32_e32 vcc, s1, v3
	v_or_b32_e32 v3, 26, v85
	v_and_b32_e32 v5, 0xffffffc0, v5
	s_movk_i32 s20, 0x65
	ds_write_b128 v193, v[8:11] offset:2048
	v_cndmask_b32_e32 v4, 0, v4, vcc
	v_xad_u32 v5, v85, s20, v5
	v_cmp_ge_i32_e32 vcc, s1, v3
	v_or_b32_e32 v3, 28, v85
	v_and_b32_e32 v6, 0xffffffc0, v6
	s_movk_i32 s20, 0x63
	ds_read_b128 v[8:11], v193 offset:4096
	v_cndmask_b32_e32 v5, 0, v5, vcc
	v_xad_u32 v6, v85, s20, v6
	v_cmp_ge_i32_e32 vcc, s1, v3
	v_or_b32_e32 v3, 30, v85
	v_and_b32_e32 v7, 0xffffffc0, v7
	s_movk_i32 s20, 0x61
	v_cndmask_b32_e32 v6, 0, v6, vcc
	v_xad_u32 v7, v85, s20, v7
	v_cmp_ge_i32_e32 vcc, s1, v3
	v_or_b32_e32 v3, 32, v85
	s_movk_i32 s20, 0x5f
	v_cndmask_b32_e32 v7, 0, v7, vcc
	ds_write_b128 v193, v[4:7] offset:3072
	ds_read_b128 v[4:7], v193 offset:5120
	s_waitcnt lgkmcnt(0)
	v_and_b32_e32 v8, 0xffffffc0, v8
	v_xad_u32 v8, v85, s20, v8
	v_cmp_ge_i32_e32 vcc, s1, v3
	v_or_b32_e32 v3, 34, v85
	v_and_b32_e32 v9, 0xffffffc0, v9
	s_movk_i32 s20, 0x5d
	v_cndmask_b32_e32 v8, 0, v8, vcc
	v_xad_u32 v9, v85, s20, v9
	v_cmp_ge_i32_e32 vcc, s1, v3
	v_or_b32_e32 v3, 36, v85
	v_and_b32_e32 v10, 0xffffffc0, v10
	s_movk_i32 s20, 0x5b
	v_cndmask_b32_e32 v9, 0, v9, vcc
	v_xad_u32 v10, v85, s20, v10
	v_cmp_ge_i32_e32 vcc, s1, v3
	v_or_b32_e32 v3, 38, v85
	v_and_b32_e32 v11, 0xffffffc0, v11
	s_movk_i32 s20, 0x59
	v_cndmask_b32_e32 v10, 0, v10, vcc
	v_xad_u32 v11, v85, s20, v11
	v_cmp_ge_i32_e32 vcc, s1, v3
	v_or_b32_e32 v3, 40, v85
	v_and_b32_e32 v4, 0xffffffc0, v4
	s_movk_i32 s20, 0x57
	v_cndmask_b32_e32 v11, 0, v11, vcc
	v_xad_u32 v4, v85, s20, v4
	v_cmp_ge_i32_e32 vcc, s1, v3
	v_or_b32_e32 v3, 42, v85
	v_and_b32_e32 v5, 0xffffffc0, v5
	s_movk_i32 s20, 0x55
	ds_write_b128 v193, v[8:11] offset:4096
	v_cndmask_b32_e32 v4, 0, v4, vcc
	v_xad_u32 v5, v85, s20, v5
	v_cmp_ge_i32_e32 vcc, s1, v3
	v_or_b32_e32 v3, 44, v85
	v_and_b32_e32 v6, 0xffffffc0, v6
	s_movk_i32 s20, 0x53
	ds_read_b128 v[8:11], v193 offset:6144
	v_cndmask_b32_e32 v5, 0, v5, vcc
	v_xad_u32 v6, v85, s20, v6
	v_cmp_ge_i32_e32 vcc, s1, v3
	v_or_b32_e32 v3, 46, v85
	v_and_b32_e32 v7, 0xffffffc0, v7
	s_movk_i32 s20, 0x51
	v_cndmask_b32_e32 v6, 0, v6, vcc
	v_xad_u32 v7, v85, s20, v7
	v_cmp_ge_i32_e32 vcc, s1, v3
	v_or_b32_e32 v3, 48, v85
	s_movk_i32 s20, 0x4f
	v_cndmask_b32_e32 v7, 0, v7, vcc
	ds_write_b128 v193, v[4:7] offset:5120
	ds_read_b128 v[4:7], v193 offset:7168
	s_waitcnt lgkmcnt(0)
	v_and_b32_e32 v8, 0xffffffc0, v8
	v_xad_u32 v8, v85, s20, v8
	v_cmp_ge_i32_e32 vcc, s1, v3
	v_or_b32_e32 v3, 50, v85
	v_and_b32_e32 v9, 0xffffffc0, v9
	s_movk_i32 s20, 0x4d
	v_cndmask_b32_e32 v8, 0, v8, vcc
	v_xad_u32 v9, v85, s20, v9
	v_cmp_ge_i32_e32 vcc, s1, v3
	v_or_b32_e32 v3, 52, v85
	v_and_b32_e32 v10, 0xffffffc0, v10
	s_movk_i32 s20, 0x4b
	v_cndmask_b32_e32 v9, 0, v9, vcc
	v_xad_u32 v10, v85, s20, v10
	v_cmp_ge_i32_e32 vcc, s1, v3
	v_or_b32_e32 v3, 54, v85
	v_and_b32_e32 v11, 0xffffffc0, v11
	s_movk_i32 s20, 0x49
	v_cndmask_b32_e32 v10, 0, v10, vcc
	v_xad_u32 v11, v85, s20, v11
	v_cmp_ge_i32_e32 vcc, s1, v3
	v_or_b32_e32 v3, 56, v85
	v_and_b32_e32 v4, 0xffffffc0, v4
	s_movk_i32 s20, 0x47
	v_cndmask_b32_e32 v11, 0, v11, vcc
	v_xad_u32 v4, v85, s20, v4
	v_cmp_ge_i32_e32 vcc, s1, v3
	v_or_b32_e32 v3, 58, v85
	v_and_b32_e32 v5, 0xffffffc0, v5
	s_movk_i32 s20, 0x45
	v_cndmask_b32_e32 v4, 0, v4, vcc
	v_xad_u32 v5, v85, s20, v5
	v_cmp_ge_i32_e32 vcc, s1, v3
	v_or_b32_e32 v3, 60, v85
	v_and_b32_e32 v6, 0xffffffc0, v6
	s_movk_i32 s20, 0x43
	v_cndmask_b32_e32 v5, 0, v5, vcc
	v_xad_u32 v6, v85, s20, v6
	v_cmp_ge_i32_e32 vcc, s1, v3
	v_or_b32_e32 v3, 62, v85
	v_and_b32_e32 v7, 0xffffffc0, v7
	s_movk_i32 s20, 0x41
	v_cndmask_b32_e32 v6, 0, v6, vcc
	v_xad_u32 v7, v85, s20, v7
	v_cmp_ge_i32_e32 vcc, s1, v3
	s_and_b32 s1, s25, 0x80
	s_add_i32 s20, s0, -1
	s_cmp_eq_u32 s1, 0
	s_cselect_b32 s1, s20, s0
	s_cselect_b32 s0, s0, s20
	s_lshr_b32 s0, s0, 1
	s_lshl_b32 s0, 1, s0
	s_lshr_b32 s1, s1, 1
	s_or_b32 s0, s0, 1
	s_lshl_b32 s1, 1, s1
	v_cndmask_b32_e32 v7, 0, v7, vcc
	s_mov_b32 s20, 13
	v_mov_b32_e32 v196, s0
	v_mov_b32_e32 v19, s1
	ds_write_b128 v193, v[8:11] offset:6144
	ds_write_b128 v193, v[4:7] offset:7168
	s_branch .LBB0_616

.Lq_preloaded:
	s_mov_b32 s69, s42
	s_mov_b32 s68, s10

.LBB0_682:
	s_cmp_lg_u32 s11, 2
	s_cbranch_scc1 .Lqh_skip
	s_and_b64 vcc, exec, s[2:3]
	s_cbranch_vccz .Lqh_skip
	s_add_i32 s0, s54, 2
	s_ashr_i32 s1, s0, 31
	s_lshl_b64 s[0:1], s[0:1], 23
	v_lshl_add_u64 v[4:5], v[170:171], 0, s[0:1]
	global_load_dwordx4 v[134:137], v[4:5], off
	global_load_dwordx4 v[138:141], v[4:5], off offset:32
	global_load_dwordx4 v[142:145], v[4:5], off offset:64
	global_load_dwordx4 v[150:153], v[4:5], off offset:96
	s_add_i32 s0, s54, 3
	s_ashr_i32 s1, s0, 31
	s_lshl_b64 s[0:1], s[0:1], 23
	v_lshl_add_u64 v[4:5], v[170:171], 0, s[0:1]
	global_load_dwordx4 v[146:149], v[4:5], off
	global_load_dwordx4 v[154:157], v[4:5], off offset:32
	global_load_dwordx4 v[158:161], v[4:5], off offset:64
	global_load_dwordx4 v[162:165], v[4:5], off offset:96
